# v11 plus scan loop o stores: four exec-wrapped 2-byte stores merged (one address calc, d16_hi stores), in-loop steps only
# baseline (speedup 1.0000x reference)
; __device__ __forceinline__ void step_part1(char* sm, int off_ut, f32x4& o) {
;   const int tid_ = opq(threadIdx.x);
;   const int lane = tid_ & 63, w = tid_ >> 6, r = lane & 15, q = lane >> 4;
;   const int mj = w >> 1, nd = w & 1;
;   const bfraw* wl = (const bfraw*)(sm + L_W);
;   const bfraw* qg = (const bfraw*)(sm + L_QG);
;   const bfraw* uT = (const bfraw*)(sm + off_ut);
;   const bfraw* St = (const bfraw*)(sm + L_ST);
;   bfraw* dltT = (bfraw*)(sm + L_DLT);
;   f32x4 dl = (f32x4){0.f, 0.f, 0.f, 0.f};
;   o = (f32x4){0.f, 0.f, 0.f, 0.f};
; #pragma unroll
;   for (int kk = 0; kk < 4; ++kk) {
;     bf16x8 sb = *(const bf16x8*)(St + (nd * 16 + r) * 136 + kk * 32 + q * 8);
;     bf16x8 aw = *(const bf16x8*)(wl + (mj * 16 + r) * 136 + kk * 32 + q * 8);
;     bf16x8 aq = *(const bf16x8*)(qg + (mj * 16 + r) * 136 + kk * 32 + q * 8);
;     dl = mfma16(aw, sb, dl);
;     o = mfma16(aq, sb, o);
;   }
;   uint2 uv = *(const uint2*)(uT + (nd * 16 + r) * 72 + mj * 16 + q * 4);
;   uint2 dv;
;   dv.x = pack2(lo2f(uv.x) - dl[0], hi2f(uv.x) - dl[1]);
;   dv.y = pack2(lo2f(uv.y) - dl[2], hi2f(uv.y) - dl[3]);
;   *(uint2*)(dltT + (nd * 16 + r) * 72 + mj * 16 + q * 4) = dv;
; }
; __device__ __forceinline__ void step_part2(const Params& p, char* sm, int off_kgt, int off_qk, int h, int s, int grow0, int nvalid,
;                                            float gl, f32x4& o, f32x4 (&S)[2]) {
;   const int tid_ = opq(threadIdx.x);
;   const int lane = tid_ & 63, w = tid_ >> 6, r = lane & 15, q = lane >> 4;
;   const int mj = w >> 1, nd = w & 1;
;   const bfraw* kgT = (const bfraw*)(sm + off_kgt);
;   const bfraw* qk = (const bfraw*)(sm + off_qk);
;   const bfraw* dltT = (const bfraw*)(sm + L_DLT);
; #pragma unroll
;   for (int g = 0; g < 4; ++g) { S[0][g] *= gl; S[1][g] *= gl; }
; #pragma unroll
;   for (int kk = 0; kk < 2; ++kk) {
;     bf16x8 d0 = *(const bf16x8*)(dltT + (r) * 72 + kk * 32 + q * 8);
;     bf16x8 d1 = *(const bf16x8*)(dltT + (16 + r) * 72 + kk * 32 + q * 8);
;     bf16x8 aqk = *(const bf16x8*)(qk + (mj * 16 + r) * 72 + kk * 32 + q * 8);
;     bf16x8 ak = *(const bf16x8*)(kgT + (w * 16 + r) * 72 + kk * 32 + q * 8);
;     o = mfma16(aqk, nd ? d1 : d0, o);
;     S[0] = mfma16(ak, d0, S[0]);
;     S[1] = mfma16(ak, d1, S[1]);
;   }
;   write_St2(S, sm);
;   bfraw* OB = (bfraw*)(p.ws + WS_B1);
; #pragma unroll
;   for (int g = 0; g < 4; ++g) {
.LBB0_1596:
	s_or_b64 exec, exec, s[10:11]
	s_add_i32 s34, s8, 2
	s_add_i32 s8, s8, 4
	s_cmpk_gt_u32 s34, 0x7e
	s_cselect_b64 s[10:11], -1, 0
	s_cmpk_lt_u32 s34, 0x7f
	s_cselect_b32 s8, s8, 0x80
	s_add_i32 s8, s8, s21
	s_lshl_b32 s8, s8, 2
	s_or_b32 s8, s8, s15
	s_waitcnt vmcnt(10)
	v_mad_u64_u32 v[24:25], s[12:13], s8, v91, v[82:83]
	v_add_co_u32_e32 v4, vcc, 0x2000, v24
	s_lshl_b64 s[12:13], s[8:9], 2
	s_nop 0
	v_addc_co_u32_e32 v5, vcc, 0, v25, vcc
	v_add_co_u32_e32 v8, vcc, 0x4000, v24
	global_load_dwordx4 v[0:3], v[24:25], off
	s_nop 0
	global_load_dwordx4 v[4:7], v[4:5], off
	v_addc_co_u32_e32 v9, vcc, 0, v25, vcc
	v_add_co_u32_e32 v12, vcc, 0x6000, v24
	s_add_u32 s12, s4, s12
	s_nop 0
	v_addc_co_u32_e32 v13, vcc, 0, v25, vcc
	v_add_co_u32_e32 v16, vcc, 0x8000, v24
	s_addc_u32 s13, s5, s13
	s_nop 0
	v_addc_co_u32_e32 v17, vcc, 0, v25, vcc
	v_add_co_u32_e32 v20, vcc, 0xa000, v24
	global_load_dwordx4 v[8:11], v[8:9], off
	s_nop 0
	global_load_dwordx4 v[12:15], v[12:13], off
	v_addc_co_u32_e32 v21, vcc, 0, v25, vcc
	v_add_co_u32_e32 v26, vcc, 0xc000, v24
	global_load_dwordx4 v[16:19], v[16:17], off
	s_nop 0
	global_load_dwordx4 v[20:23], v[20:21], off
	v_addc_co_u32_e32 v27, vcc, 0, v25, vcc
	v_lshl_add_u64 v[24:25], v[24:25], 0, s[0:1]
	v_lshl_add_u64 v[24:25], v[76:77], 1, v[24:25]
	v_add_co_u32_e32 v24, vcc, 0xe000, v24
	v_mov_b32_e32 v72, v224
	s_nop 0
	v_addc_co_u32_e32 v25, vcc, 0, v25, vcc
	global_load_dwordx4 v[28:31], v[26:27], off
	s_nop 0
	global_load_dwordx4 v[24:27], v[24:25], off
	s_waitcnt vmcnt(17)
	v_pk_mul_f32 v[68:69], v[80:81], v[68:69] op_sel_hi:[0,1]
	global_load_dword v92, v81, s[12:13]
	s_waitcnt lgkmcnt(0)
	s_barrier
	v_pk_mul_f32 v[70:71], v[80:81], v[70:71] op_sel_hi:[0,1]
	v_ashrrev_i32_e32 v118, 3, v72
	v_and_b32_e32 v79, 15, v72
	v_bfe_u32 v84, v72, 4, 2
	v_lshrrev_b32_e32 v85, 2, v72
	v_bfi_b32 v72, -16, v118, v72
	v_lshlrev_b32_e32 v93, 4, v84
	v_mul_lo_u32 v72, v72, s30
	v_add3_u32 v114, 0, v72, v93
	ds_read_b128 v[72:75], v114
	v_and_or_b32 v79, v85, 16, v79
	v_mul_u32_u24_e32 v85, 0x110, v79
	v_add3_u32 v85, s16, v85, v93
	ds_read_b128 v[94:97], v85
	ds_read_b128 v[98:101], v85 offset:64
	ds_read_b128 v[102:105], v114 offset:64
	s_waitcnt lgkmcnt(2)
	v_mfma_f32_16x16x32_bf16 v[72:75], v[72:75], v[94:97], 0
	ds_read_b128 v[106:109], v114 offset:17408
	ds_read_b128 v[110:113], v114 offset:17472
	v_mul_u32_u24_e32 v79, 0x48, v79
	v_lshlrev_b32_e32 v93, 3, v84
	s_waitcnt lgkmcnt(2)
	v_mfma_f32_16x16x32_bf16 v[72:75], v[102:105], v[98:101], v[72:75]
	ds_read_b128 v[102:105], v114 offset:128
	v_and_b32_e32 v84, -16, v118
	v_lshlrev_b32_e32 v79, 1, v79
	s_waitcnt lgkmcnt(2)
	v_mfma_f32_16x16x32_bf16 v[94:97], v[106:109], v[94:97], 0
	v_mul_f32_e64 v64, v80, v64
	v_mul_f32_e64 v65, v80, v65
	v_pk_mul_f32 v[66:67], v[80:81], v[66:67] op_sel_hi:[0,1]
	s_waitcnt lgkmcnt(1)
	v_mfma_f32_16x16x32_bf16 v[94:97], v[110:113], v[98:101], v[94:97]
	ds_read_b128 v[98:101], v85 offset:128
	ds_read_b128 v[106:109], v85 offset:192
	ds_read_b128 v[110:113], v114 offset:192
	v_add_u32_e32 v85, 0, v79
	s_waitcnt lgkmcnt(2)
	v_mfma_f32_16x16x32_bf16 v[72:75], v[102:105], v[98:101], v[72:75]
	ds_read_b128 v[102:105], v114 offset:17536
	ds_read_b128 v[114:117], v114 offset:17600
	s_waitcnt lgkmcnt(1)
	v_mfma_f32_16x16x32_bf16 v[94:97], v[102:105], v[98:101], v[94:97]
	v_lshlrev_b32_e32 v100, 1, v84
	v_add3_u32 v84, v85, v100, v93
	ds_read_b64 v[84:85], v84 offset:62464
	v_mfma_f32_16x16x32_bf16 v[72:75], v[110:113], v[106:109], v[72:75]
	s_waitcnt lgkmcnt(0)
	v_lshlrev_b32_e32 v98, 16, v84
	v_and_b32_e32 v99, 0xffff0000, v84
	v_lshlrev_b32_e32 v84, 16, v85
	v_and_b32_e32 v85, 0xffff0000, v85
	s_nop 2
	v_pk_add_f32 v[72:73], v[98:99], v[72:73] neg_lo:[0,1] neg_hi:[0,1]
	v_pk_add_f32 v[74:75], v[84:85], v[74:75] neg_lo:[0,1] neg_hi:[0,1]
	v_cvt_pk_bf16_f32 v72, v72, v73
	v_cvt_pk_bf16_f32 v73, v74, v75
	v_add_u32_e32 v74, s17, v79
	v_add3_u32 v74, v74, v100, v93
	ds_write_b64 v74, v[72:73]
	v_mov_b32_e32 v72, v224
	s_waitcnt lgkmcnt(0)
	s_barrier
	v_mfma_f32_16x16x32_bf16 v[94:97], v[114:117], v[106:109], v[94:97]
	v_ashrrev_i32_e32 v85, 3, v72
	v_ashrrev_i32_e32 v73, 6, v72
	v_and_b32_e32 v93, 15, v72
	v_bfe_u32 v79, v72, 4, 2
	v_bfi_b32 v72, -16, v85, v72
	v_lshlrev_b32_e32 v75, 4, v79
	v_mul_lo_u32 v72, v72, s31
	v_mul_u32_u24_e32 v74, 0x90, v93
	v_add3_u32 v122, 0, v72, v75
	v_lshl_or_b32 v72, v73, 4, v93
	v_and_b32_e32 v126, 1, v73
	v_add3_u32 v84, s17, v74, v75
	v_mul_lo_u32 v72, v72, s31
	v_add3_u32 v127, 0, v72, v75
	ds_read_b128 v[72:75], v84
	ds_read_b128 v[98:101], v84 offset:2304
	ds_read_b128 v[102:105], v122 offset:53248
	ds_read_b128 v[106:109], v127 offset:34816
	ds_read_b128 v[110:113], v84 offset:64
	ds_read_b128 v[114:117], v84 offset:2368
	v_cmp_eq_u32_e32 vcc, 0, v126
	ds_read_b128 v[122:125], v122 offset:53312
	s_waitcnt lgkmcnt(3)
	v_mfma_f32_16x16x32_bf16 v[68:71], v[106:109], v[72:75], v[68:71]
	v_cndmask_b32_e32 v121, v101, v75, vcc
	v_cndmask_b32_e32 v120, v100, v74, vcc
	v_cndmask_b32_e32 v119, v99, v73, vcc
	v_cndmask_b32_e32 v118, v98, v72, vcc
	v_mfma_f32_16x16x32_bf16 v[64:67], v[106:109], v[98:101], v[64:67]
	s_waitcnt lgkmcnt(1)
	v_cndmask_b32_e32 v75, v117, v113, vcc
	v_cndmask_b32_e32 v74, v116, v112, vcc
	v_cndmask_b32_e32 v73, v115, v111, vcc
	v_mfma_f32_16x16x32_bf16 v[94:97], v[102:105], v[118:121], v[94:97]
	ds_read_b128 v[102:105], v127 offset:34880
	v_cndmask_b32_e32 v72, v114, v110, vcc
	v_mov_b32_e32 v84, v224
	s_waitcnt lgkmcnt(0)
	v_mfma_f32_16x16x32_bf16 v[68:71], v[102:105], v[110:113], v[68:71]
	v_and_b32_e32 v80, -16, v85
	v_and_b32_e32 v85, 15, v84
	v_mfma_f32_16x16x32_bf16 v[72:75], v[122:125], v[72:75], v[94:97]
	v_mul_u32_u24_e32 v85, 0x110, v85
	v_lshl_or_b32 v79, v79, 2, v80
	v_lshlrev_b32_e32 v80, 5, v126
	v_ashrrev_i32_e32 v94, 2, v84
	v_mfma_f32_16x16x32_bf16 v[64:67], v[102:105], v[114:117], v[64:67]
	v_lshlrev_b32_e32 v94, 1, v94
	v_and_b32_e32 v94, 0xffffffe0, v94
	v_lshrrev_b32_e32 v84, 1, v84
	v_add_u32_e32 v94, s16, v94
	v_and_b32_e32 v84, 24, v84
	v_add3_u32 v94, v94, v84, v85
	v_cvt_pk_bf16_f32 v85, v70, v71
	v_cvt_pk_bf16_f32 v84, v68, v69
	ds_write_b64 v94, v[84:85]
	v_cvt_pk_bf16_f32 v85, v66, v67
	v_cvt_pk_bf16_f32 v84, v64, v65
	ds_write_b64 v94, v[84:85] offset:4352
	v_lshl_add_u64 v[84:85], s[6:7], 0, v[80:81]
	v_lshlrev_b32_e32 v80, 1, v93
	v_lshl_add_u64 v[84:85], v[84:85], 0, v[80:81]
	v_cmp_gt_i32_e32 vcc, 64, v79
	s_add_i32 s8, s18, s33
	v_add_u32_e32 v94, s8, v79
	v_add_u32_e32 v94, 0x51, v94
	v_ashrrev_i32_e32 v95, 31, v94
	v_lshlrev_b64 v[94:95], 12, v[94:95]
	v_lshl_add_u64 v[94:95], v[84:85], 0, v[94:95]
	v_cvt_pk_bf16_f32 v72, v72, v73
	v_cvt_pk_bf16_f32 v74, v74, v75
	s_mov_b64 s[98:99], 0x2000
	global_store_short v[94:95], v72, off offset:-4096
	global_store_short_d16_hi v[94:95], v72, off
	v_lshl_add_u64 v[94:95], v[94:95], 0, s[98:99]
	global_store_short v[94:95], v74, off offset:-4096
	global_store_short_d16_hi v[94:95], v74, off
	s_cmpk_eq_i32 s33, 0x1f80
	s_cbranch_scc1 .LBB0_1592
	s_waitcnt vmcnt(17)
	ds_write_b128 v86, v[32:35]
	s_waitcnt vmcnt(16)
	ds_write_b128 v86, v[36:39] offset:8704
	s_waitcnt vmcnt(15)
	ds_write_b128 v86, v[40:43] offset:17408
	s_waitcnt vmcnt(14)
	ds_write_b128 v86, v[44:47] offset:26112
	s_waitcnt vmcnt(13)
	ds_write_b128 v88, v[48:51]
	s_waitcnt vmcnt(12)
	ds_write_b128 v89, v[52:55] offset:9216
	s_waitcnt vmcnt(11)
	ds_write_b128 v90, v[60:63]
	s_and_saveexec_b64 s[12:13], s[2:3]
	s_cbranch_execz .LBB0_1607
	s_waitcnt vmcnt(10)
	ds_write_b128 v87, v[56:59] offset:62464
; __device__ __forceinline__ void step_part1(char* sm, int off_ut, f32x4& o) {
;   const int tid_ = opq(threadIdx.x);
;   const int lane = tid_ & 63, w = tid_ >> 6, r = lane & 15, q = lane >> 4;
;   const int mj = w >> 1, nd = w & 1;
;   const bfraw* wl = (const bfraw*)(sm + L_W);
;   const bfraw* qg = (const bfraw*)(sm + L_QG);
;   const bfraw* uT = (const bfraw*)(sm + off_ut);
;   const bfraw* St = (const bfraw*)(sm + L_ST);
;   bfraw* dltT = (bfraw*)(sm + L_DLT);
;   f32x4 dl = (f32x4){0.f, 0.f, 0.f, 0.f};
;   o = (f32x4){0.f, 0.f, 0.f, 0.f};
; #pragma unroll
;   for (int kk = 0; kk < 4; ++kk) {
;     bf16x8 sb = *(const bf16x8*)(St + (nd * 16 + r) * 136 + kk * 32 + q * 8);
;     bf16x8 aw = *(const bf16x8*)(wl + (mj * 16 + r) * 136 + kk * 32 + q * 8);
;     bf16x8 aq = *(const bf16x8*)(qg + (mj * 16 + r) * 136 + kk * 32 + q * 8);
;     dl = mfma16(aw, sb, dl);
;     o = mfma16(aq, sb, o);
;   }
;   uint2 uv = *(const uint2*)(uT + (nd * 16 + r) * 72 + mj * 16 + q * 4);
;   uint2 dv;
;   dv.x = pack2(lo2f(uv.x) - dl[0], hi2f(uv.x) - dl[1]);
;   dv.y = pack2(lo2f(uv.y) - dl[2], hi2f(uv.y) - dl[3]);
;   *(uint2*)(dltT + (nd * 16 + r) * 72 + mj * 16 + q * 4) = dv;
; }
; __device__ __forceinline__ void step_part2(const Params& p, char* sm, int off_kgt, int off_qk, int h, int s, int grow0, int nvalid,
;                                            float gl, f32x4& o, f32x4 (&S)[2]) {
;   const int tid_ = opq(threadIdx.x);
;   const int lane = tid_ & 63, w = tid_ >> 6, r = lane & 15, q = lane >> 4;
;   const int mj = w >> 1, nd = w & 1;
;   const bfraw* kgT = (const bfraw*)(sm + off_kgt);
;   const bfraw* qk = (const bfraw*)(sm + off_qk);
;   const bfraw* dltT = (const bfraw*)(sm + L_DLT);
; #pragma unroll
;   for (int g = 0; g < 4; ++g) { S[0][g] *= gl; S[1][g] *= gl; }
; #pragma unroll
;   for (int kk = 0; kk < 2; ++kk) {
;     bf16x8 d0 = *(const bf16x8*)(dltT + (r) * 72 + kk * 32 + q * 8);
;     bf16x8 d1 = *(const bf16x8*)(dltT + (16 + r) * 72 + kk * 32 + q * 8);
;     bf16x8 aqk = *(const bf16x8*)(qk + (mj * 16 + r) * 72 + kk * 32 + q * 8);
;     bf16x8 ak = *(const bf16x8*)(kgT + (w * 16 + r) * 72 + kk * 32 + q * 8);
;     o = mfma16(aqk, nd ? d1 : d0, o);
;     S[0] = mfma16(ak, d0, S[0]);
;     S[1] = mfma16(ak, d1, S[1]);
;   }
;   write_St2(S, sm);
;   bfraw* OB = (bfraw*)(p.ws + WS_B1);
; #pragma unroll
;   for (int g = 0; g < 4; ++g) {
.LBB0_1607:
	s_or_b64 exec, exec, s[12:13]
	s_min_u32 s8, s34, 0x7d
	s_add_i32 s8, s8, s28
	s_lshl_b32 s8, s8, 2
	s_or_b32 s8, s8, s15
	s_waitcnt vmcnt(10)
	v_mov_b32_e32 v78, v225
	v_mad_u64_u32 v[56:57], s[12:13], s8, v91, v[82:83]
	v_add_co_u32_e32 v36, vcc, 0x2000, v56
	s_lshl_b32 s8, s8, 2
	s_nop 0
	v_addc_co_u32_e32 v37, vcc, 0, v57, vcc
	v_add_co_u32_e32 v40, vcc, 0x4000, v56
	global_load_dwordx4 v[32:35], v[56:57], off
	s_nop 0
	global_load_dwordx4 v[36:39], v[36:37], off
	v_addc_co_u32_e32 v41, vcc, 0, v57, vcc
	v_add_co_u32_e32 v44, vcc, 0x6000, v56
	v_mov_b32_e32 v72, s8
	s_nop 0
	v_addc_co_u32_e32 v45, vcc, 0, v57, vcc
	v_add_co_u32_e32 v48, vcc, 0x8000, v56
	global_load_dwordx4 v[40:43], v[40:41], off
	s_nop 0
	global_load_dwordx4 v[44:47], v[44:45], off
	v_addc_co_u32_e32 v49, vcc, 0, v57, vcc
	v_add_co_u32_e32 v52, vcc, 0xa000, v56
	s_nop 1
	v_addc_co_u32_e32 v53, vcc, 0, v57, vcc
	v_add_co_u32_e32 v58, vcc, 0xc000, v56
	global_load_dwordx4 v[48:51], v[48:49], off
	s_nop 0
	global_load_dwordx4 v[52:55], v[52:53], off
	v_addc_co_u32_e32 v59, vcc, 0, v57, vcc
	v_lshl_add_u64 v[56:57], v[56:57], 0, s[0:1]
	v_lshl_add_u64 v[56:57], v[76:77], 1, v[56:57]
	v_add_co_u32_e32 v56, vcc, 0xe000, v56
	s_nop 1
	v_addc_co_u32_e32 v57, vcc, 0, v57, vcc
	global_load_dwordx4 v[60:63], v[58:59], off
	s_nop 0
	global_load_dwordx4 v[56:59], v[56:57], off
	s_nop 0
	global_load_dword v225, v72, s[4:5]
	v_mov_b32_e32 v72, v224
	s_waitcnt lgkmcnt(0)
	s_barrier
	s_nop 0
	v_ashrrev_i32_e32 v118, 3, v72
	v_and_b32_e32 v79, 15, v72
	v_bfe_u32 v80, v72, 4, 2
	v_lshrrev_b32_e32 v85, 2, v72
	v_bfi_b32 v72, -16, v118, v72
	v_lshlrev_b32_e32 v93, 4, v80
	v_mul_lo_u32 v72, v72, s30
	v_add3_u32 v114, 0, v72, v93
	ds_read_b128 v[72:75], v114
	v_and_or_b32 v79, v85, 16, v79
	v_mul_u32_u24_e32 v85, 0x110, v79
	v_add3_u32 v85, s16, v85, v93
	ds_read_b128 v[94:97], v85
	ds_read_b128 v[98:101], v85 offset:64
	ds_read_b128 v[102:105], v114 offset:64
	s_waitcnt lgkmcnt(2)
	v_mfma_f32_16x16x32_bf16 v[72:75], v[72:75], v[94:97], 0
	ds_read_b128 v[106:109], v114 offset:17408
	ds_read_b128 v[110:113], v114 offset:17472
	v_mul_u32_u24_e32 v79, 0x48, v79
	v_lshlrev_b32_e32 v79, 1, v79
	s_waitcnt lgkmcnt(2)
	v_mfma_f32_16x16x32_bf16 v[72:75], v[102:105], v[98:101], v[72:75]
	ds_read_b128 v[102:105], v114 offset:128
	v_lshlrev_b32_e32 v80, 3, v80
	v_add_u32_e32 v93, 0, v79
	s_waitcnt lgkmcnt(2)
	v_mfma_f32_16x16x32_bf16 v[94:97], v[106:109], v[94:97], 0
	s_waitcnt lgkmcnt(1)
	v_mfma_f32_16x16x32_bf16 v[94:97], v[110:113], v[98:101], v[94:97]
	ds_read_b128 v[98:101], v85 offset:128
	ds_read_b128 v[106:109], v85 offset:192
	ds_read_b128 v[110:113], v114 offset:192
	v_and_b32_e32 v85, -16, v118
	v_lshlrev_b32_e32 v85, 1, v85
	s_waitcnt lgkmcnt(2)
	v_mfma_f32_16x16x32_bf16 v[72:75], v[102:105], v[98:101], v[72:75]
	ds_read_b128 v[102:105], v114 offset:17536
	ds_read_b128 v[114:117], v114 offset:17600
	v_add3_u32 v93, v93, v85, v80
	s_waitcnt lgkmcnt(1)
	v_mfma_f32_16x16x32_bf16 v[94:97], v[102:105], v[98:101], v[94:97]
	ds_read_b64 v[98:99], v93 offset:62464
	s_waitcnt lgkmcnt(0)
	v_lshlrev_b32_e32 v100, 16, v98
	v_mfma_f32_16x16x32_bf16 v[72:75], v[110:113], v[106:109], v[72:75]
	v_and_b32_e32 v101, 0xffff0000, v98
	v_lshlrev_b32_e32 v98, 16, v99
	v_and_b32_e32 v99, 0xffff0000, v99
	v_mfma_f32_16x16x32_bf16 v[94:97], v[114:117], v[106:109], v[94:97]
	s_nop 3
	v_add_f32_e64 v72, v100, -v72
	v_add_f32_e64 v73, v101, -v73
	v_pk_add_f32 v[74:75], v[98:99], v[74:75] neg_lo:[0,1] neg_hi:[0,1]
	v_cvt_pk_bf16_f32 v72, v72, v73
	v_cvt_pk_bf16_f32 v73, v74, v75
	v_add_u32_e32 v74, s17, v79
	v_add3_u32 v74, v74, v85, v80
	ds_write_b64 v74, v[72:73]
	v_mov_b32_e32 v72, v224
	s_waitcnt lgkmcnt(0)
	s_barrier
	s_nop 0
	v_ashrrev_i32_e32 v85, 3, v72
	v_ashrrev_i32_e32 v73, 6, v72
	v_and_b32_e32 v93, 15, v72
	v_bfe_u32 v80, v72, 4, 2
	v_bfi_b32 v72, -16, v85, v72
	v_lshlrev_b32_e32 v75, 4, v80
	v_mul_lo_u32 v72, v72, s31
	v_mul_u32_u24_e32 v74, 0x90, v93
	v_add3_u32 v122, s20, v72, v75
	v_lshl_or_b32 v72, v73, 4, v93
	v_and_b32_e32 v126, 1, v73
	v_add3_u32 v79, s17, v74, v75
	v_mul_lo_u32 v72, v72, s31
	v_add3_u32 v127, s19, v72, v75
	ds_read_b128 v[72:75], v79
	ds_read_b128 v[98:101], v79 offset:2304
	ds_read_b128 v[102:105], v122
	ds_read_b128 v[106:109], v127
	ds_read_b128 v[110:113], v79 offset:64
	ds_read_b128 v[114:117], v79 offset:2368
	v_cmp_eq_u32_e32 vcc, 0, v126
	ds_read_b128 v[122:125], v122 offset:64
	s_waitcnt vmcnt(18)
	v_pk_mul_f32 v[70:71], v[78:79], v[70:71] op_sel_hi:[0,1]
	s_waitcnt lgkmcnt(5)
	v_cndmask_b32_e32 v121, v101, v75, vcc
	v_cndmask_b32_e32 v120, v100, v74, vcc
	v_cndmask_b32_e32 v119, v99, v73, vcc
	v_cndmask_b32_e32 v118, v98, v72, vcc
	v_pk_mul_f32 v[68:69], v[78:79], v[68:69] op_sel_hi:[0,1]
	v_pk_mul_f32 v[66:67], v[78:79], v[66:67] op_sel_hi:[0,1]
	s_waitcnt lgkmcnt(4)
	v_mfma_f32_16x16x32_bf16 v[94:97], v[102:105], v[118:121], v[94:97]
	ds_read_b128 v[102:105], v127 offset:64
	v_pk_mul_f32 v[64:65], v[78:79], v[64:65] op_sel_hi:[0,1]
	v_mov_b32_e32 v78, v224
	s_waitcnt lgkmcnt(4)
	v_mfma_f32_16x16x32_bf16 v[68:71], v[106:109], v[72:75], v[68:71]
	s_waitcnt lgkmcnt(2)
	v_cndmask_b32_e32 v75, v117, v113, vcc
	v_cndmask_b32_e32 v74, v116, v112, vcc
	v_cndmask_b32_e32 v73, v115, v111, vcc
	v_mfma_f32_16x16x32_bf16 v[64:67], v[106:109], v[98:101], v[64:67]
	v_cndmask_b32_e32 v72, v114, v110, vcc
	v_and_b32_e32 v85, -16, v85
	s_waitcnt lgkmcnt(0)
	v_mfma_f32_16x16x32_bf16 v[68:71], v[102:105], v[110:113], v[68:71]
	v_and_b32_e32 v79, 15, v78
	v_mul_u32_u24_e32 v79, 0x110, v79
	v_lshl_or_b32 v85, v80, 2, v85
	v_mfma_f32_16x16x32_bf16 v[72:75], v[122:125], v[72:75], v[94:97]
	v_lshlrev_b32_e32 v80, 5, v126
	v_cmp_gt_i32_e32 vcc, 64, v85
	s_nop 0
	v_ashrrev_i32_e32 v94, 2, v78
	v_mfma_f32_16x16x32_bf16 v[64:67], v[102:105], v[114:117], v[64:67]
	v_lshlrev_b32_e32 v94, 1, v94
	v_and_b32_e32 v94, 0xffffffe0, v94
	v_lshrrev_b32_e32 v78, 1, v78
	v_add_u32_e32 v94, s16, v94
	v_and_b32_e32 v78, 24, v78
	v_add3_u32 v94, v94, v78, v79
	v_cvt_pk_bf16_f32 v79, v70, v71
	v_cvt_pk_bf16_f32 v78, v68, v69
	ds_write_b64 v94, v[78:79]
	v_cvt_pk_bf16_f32 v79, v66, v67
	v_cvt_pk_bf16_f32 v78, v64, v65
	ds_write_b64 v94, v[78:79] offset:4352
	v_lshl_add_u64 v[78:79], s[6:7], 0, v[80:81]
	v_lshlrev_b32_e32 v80, 1, v93
	v_lshl_add_u64 v[78:79], v[78:79], 0, v[80:81]
	s_add_i32 s8, s18, s33
	v_add_u32_e32 v94, s8, v85
	v_add_u32_e32 v94, 0x91, v94
	v_ashrrev_i32_e32 v95, 31, v94
	v_lshlrev_b64 v[94:95], 12, v[94:95]
	v_lshl_add_u64 v[94:95], v[78:79], 0, v[94:95]
	v_cvt_pk_bf16_f32 v72, v72, v73
	v_cvt_pk_bf16_f32 v74, v74, v75
	s_mov_b64 s[98:99], 0x2000
	global_store_short v[94:95], v72, off offset:-4096
	global_store_short_d16_hi v[94:95], v72, off
	v_lshl_add_u64 v[94:95], v[94:95], 0, s[98:99]
	global_store_short v[94:95], v74, off offset:-4096
	global_store_short_d16_hi v[94:95], v74, off
	s_andn2_b64 vcc, exec, s[10:11]
	s_addk_i32 s33, 0x80
	s_cbranch_vccnz .LBB0_1593

; __device__ __forceinline__ void step_part1(char* sm, int off_ut, f32x4& o) {
;   const int tid_ = opq(threadIdx.x);
;   const int lane = tid_ & 63, w = tid_ >> 6, r = lane & 15, q = lane >> 4;
;   const int mj = w >> 1, nd = w & 1;
;   const bfraw* wl = (const bfraw*)(sm + L_W);
;   const bfraw* qg = (const bfraw*)(sm + L_QG);
;   const bfraw* uT = (const bfraw*)(sm + off_ut);
;   const bfraw* St = (const bfraw*)(sm + L_ST);
;   bfraw* dltT = (bfraw*)(sm + L_DLT);
;   f32x4 dl = (f32x4){0.f, 0.f, 0.f, 0.f};
;   o = (f32x4){0.f, 0.f, 0.f, 0.f};
; #pragma unroll
;   for (int kk = 0; kk < 4; ++kk) {
;     bf16x8 sb = *(const bf16x8*)(St + (nd * 16 + r) * 136 + kk * 32 + q * 8);
;     bf16x8 aw = *(const bf16x8*)(wl + (mj * 16 + r) * 136 + kk * 32 + q * 8);
;     bf16x8 aq = *(const bf16x8*)(qg + (mj * 16 + r) * 136 + kk * 32 + q * 8);
;     dl = mfma16(aw, sb, dl);
;     o = mfma16(aq, sb, o);
;   }
;   uint2 uv = *(const uint2*)(uT + (nd * 16 + r) * 72 + mj * 16 + q * 4);
;   uint2 dv;
;   dv.x = pack2(lo2f(uv.x) - dl[0], hi2f(uv.x) - dl[1]);
;   dv.y = pack2(lo2f(uv.y) - dl[2], hi2f(uv.y) - dl[3]);
;   *(uint2*)(dltT + (nd * 16 + r) * 72 + mj * 16 + q * 4) = dv;
; }
; __device__ __forceinline__ void step_part2(const Params& p, char* sm, int off_kgt, int off_qk, int h, int s, int grow0, int nvalid,
;                                            float gl, f32x4& o, f32x4 (&S)[2]) {
;   const int tid_ = opq(threadIdx.x);
;   const int lane = tid_ & 63, w = tid_ >> 6, r = lane & 15, q = lane >> 4;
;   const int mj = w >> 1, nd = w & 1;
;   const bfraw* kgT = (const bfraw*)(sm + off_kgt);
;   const bfraw* qk = (const bfraw*)(sm + off_qk);
;   const bfraw* dltT = (const bfraw*)(sm + L_DLT);
; #pragma unroll
;   for (int g = 0; g < 4; ++g) { S[0][g] *= gl; S[1][g] *= gl; }
; #pragma unroll
;   for (int kk = 0; kk < 2; ++kk) {
;     bf16x8 d0 = *(const bf16x8*)(dltT + (r) * 72 + kk * 32 + q * 8);
;     bf16x8 d1 = *(const bf16x8*)(dltT + (16 + r) * 72 + kk * 32 + q * 8);
;     bf16x8 aqk = *(const bf16x8*)(qk + (mj * 16 + r) * 72 + kk * 32 + q * 8);
;     bf16x8 ak = *(const bf16x8*)(kgT + (w * 16 + r) * 72 + kk * 32 + q * 8);
;     o = mfma16(aqk, nd ? d1 : d0, o);
;     S[0] = mfma16(ak, d0, S[0]);
;     S[1] = mfma16(ak, d1, S[1]);
;   }
;   write_St2(S, sm);
;   bfraw* OB = (bfraw*)(p.ws + WS_B1);
; #pragma unroll
;   for (int g = 0; g < 4; ++g) {
.LBB0_4354:
	s_or_b64 exec, exec, s[10:11]
	s_add_i32 s34, s8, 2
	s_add_i32 s8, s8, 4
	s_cmpk_gt_u32 s34, 0x7e
	s_cselect_b64 s[10:11], -1, 0
	s_cmpk_lt_u32 s34, 0x7f
	s_cselect_b32 s8, s8, 0x80
	s_add_i32 s8, s8, s21
	s_lshl_b32 s8, s8, 2
	s_or_b32 s8, s8, s15
	s_waitcnt vmcnt(10)
	v_mad_u64_u32 v[24:25], s[12:13], s8, v91, v[82:83]
	v_add_co_u32_e32 v8, vcc, 0x2000, v24
	s_lshl_b64 s[12:13], s[8:9], 2
	s_nop 0
	v_addc_co_u32_e32 v9, vcc, 0, v25, vcc
	global_load_dwordx4 v[0:3], v[24:25], off
	global_load_dwordx4 v[4:7], v[8:9], off
	v_add_co_u32_e32 v8, vcc, 0x4000, v24
	s_add_u32 s12, s4, s12
	s_nop 0
	v_addc_co_u32_e32 v9, vcc, 0, v25, vcc
	v_add_co_u32_e32 v12, vcc, 0x6000, v24
	s_addc_u32 s13, s5, s13
	s_nop 0
	v_addc_co_u32_e32 v13, vcc, 0, v25, vcc
	v_add_co_u32_e32 v16, vcc, 0x8000, v24
	global_load_dwordx4 v[8:11], v[8:9], off
	s_nop 0
	global_load_dwordx4 v[12:15], v[12:13], off
	v_addc_co_u32_e32 v17, vcc, 0, v25, vcc
	v_add_co_u32_e32 v20, vcc, 0xa000, v24
	v_mov_b32_e32 v72, v224
	s_nop 0
	v_addc_co_u32_e32 v21, vcc, 0, v25, vcc
	v_add_co_u32_e32 v26, vcc, 0xc000, v24
	global_load_dwordx4 v[16:19], v[16:17], off
	s_nop 0
	global_load_dwordx4 v[20:23], v[20:21], off
	v_addc_co_u32_e32 v27, vcc, 0, v25, vcc
	v_lshl_add_u64 v[24:25], v[24:25], 0, s[0:1]
	v_lshl_add_u64 v[24:25], v[76:77], 1, v[24:25]
	v_add_co_u32_e32 v24, vcc, 0xe000, v24
	s_waitcnt vmcnt(15)
	v_pk_mul_f32 v[68:69], v[80:81], v[68:69] op_sel_hi:[0,1]
	v_addc_co_u32_e32 v25, vcc, 0, v25, vcc
	global_load_dwordx4 v[28:31], v[26:27], off
	s_nop 0
	global_load_dwordx4 v[24:27], v[24:25], off
	v_pk_mul_f32 v[70:71], v[80:81], v[70:71] op_sel_hi:[0,1]
	global_load_dword v92, v81, s[12:13]
	s_waitcnt lgkmcnt(0)
	s_barrier
	v_pk_mul_f32 v[64:65], v[80:81], v[64:65] op_sel_hi:[0,1]
	v_ashrrev_i32_e32 v118, 3, v72
	v_and_b32_e32 v79, 15, v72
	v_bfe_u32 v84, v72, 4, 2
	v_lshrrev_b32_e32 v85, 2, v72
	v_bfi_b32 v72, -16, v118, v72
	v_lshlrev_b32_e32 v93, 4, v84
	v_mul_lo_u32 v72, v72, s30
	v_add3_u32 v114, 0, v72, v93
	ds_read_b128 v[72:75], v114
	v_and_or_b32 v79, v85, 16, v79
	v_mul_u32_u24_e32 v85, 0x110, v79
	v_add3_u32 v85, s16, v85, v93
	ds_read_b128 v[94:97], v85
	ds_read_b128 v[98:101], v85 offset:64
	ds_read_b128 v[102:105], v114 offset:64
	s_waitcnt lgkmcnt(2)
	v_mfma_f32_16x16x32_bf16 v[72:75], v[72:75], v[94:97], 0
	ds_read_b128 v[106:109], v114 offset:17408
	ds_read_b128 v[110:113], v114 offset:17472
	v_mul_u32_u24_e32 v79, 0x48, v79
	v_lshlrev_b32_e32 v93, 3, v84
	s_waitcnt lgkmcnt(2)
	v_mfma_f32_16x16x32_bf16 v[72:75], v[102:105], v[98:101], v[72:75]
	ds_read_b128 v[102:105], v114 offset:128
	v_and_b32_e32 v84, -16, v118
	v_lshlrev_b32_e32 v79, 1, v79
	s_waitcnt lgkmcnt(2)
	v_mfma_f32_16x16x32_bf16 v[94:97], v[106:109], v[94:97], 0
	v_mul_f32_e64 v66, v80, v66
	v_mul_f32_e64 v67, v80, v67
	s_waitcnt lgkmcnt(1)
	v_mfma_f32_16x16x32_bf16 v[94:97], v[110:113], v[98:101], v[94:97]
	ds_read_b128 v[98:101], v85 offset:128
	ds_read_b128 v[106:109], v85 offset:192
	ds_read_b128 v[110:113], v114 offset:192
	v_add_u32_e32 v85, 0, v79
	s_waitcnt lgkmcnt(2)
	v_mfma_f32_16x16x32_bf16 v[72:75], v[102:105], v[98:101], v[72:75]
	ds_read_b128 v[102:105], v114 offset:17536
	ds_read_b128 v[114:117], v114 offset:17600
	s_waitcnt lgkmcnt(1)
	v_mfma_f32_16x16x32_bf16 v[94:97], v[102:105], v[98:101], v[94:97]
	v_lshlrev_b32_e32 v100, 1, v84
	v_add3_u32 v84, v85, v100, v93
	ds_read_b64 v[84:85], v84 offset:62464
	v_mfma_f32_16x16x32_bf16 v[72:75], v[110:113], v[106:109], v[72:75]
	s_waitcnt lgkmcnt(0)
	v_lshlrev_b32_e32 v98, 16, v84
	v_and_b32_e32 v99, 0xffff0000, v84
	v_lshlrev_b32_e32 v84, 16, v85
	v_and_b32_e32 v85, 0xffff0000, v85
	s_nop 2
	v_pk_add_f32 v[72:73], v[98:99], v[72:73] neg_lo:[0,1] neg_hi:[0,1]
	v_pk_add_f32 v[74:75], v[84:85], v[74:75] neg_lo:[0,1] neg_hi:[0,1]
	v_cvt_pk_bf16_f32 v72, v72, v73
	v_cvt_pk_bf16_f32 v73, v74, v75
	v_add_u32_e32 v74, s17, v79
	v_add3_u32 v74, v74, v100, v93
	ds_write_b64 v74, v[72:73]
	v_mov_b32_e32 v72, v224
	s_waitcnt lgkmcnt(0)
	s_barrier
	v_mfma_f32_16x16x32_bf16 v[94:97], v[114:117], v[106:109], v[94:97]
	v_ashrrev_i32_e32 v85, 3, v72
	v_ashrrev_i32_e32 v73, 6, v72
	v_and_b32_e32 v93, 15, v72
	v_bfe_u32 v79, v72, 4, 2
	v_bfi_b32 v72, -16, v85, v72
	v_lshlrev_b32_e32 v75, 4, v79
	v_mul_lo_u32 v72, v72, s31
	v_mul_u32_u24_e32 v74, 0x90, v93
	v_add3_u32 v122, 0, v72, v75
	v_lshl_or_b32 v72, v73, 4, v93
	v_and_b32_e32 v126, 1, v73
	v_add3_u32 v84, s17, v74, v75
	v_mul_lo_u32 v72, v72, s31
	v_add3_u32 v127, 0, v72, v75
	ds_read_b128 v[72:75], v84
	ds_read_b128 v[98:101], v84 offset:2304
	ds_read_b128 v[102:105], v122 offset:53248
	ds_read_b128 v[106:109], v127 offset:34816
	ds_read_b128 v[110:113], v84 offset:64
	ds_read_b128 v[114:117], v84 offset:2368
	v_cmp_eq_u32_e32 vcc, 0, v126
	ds_read_b128 v[122:125], v122 offset:53312
	s_waitcnt lgkmcnt(3)
	v_mfma_f32_16x16x32_bf16 v[68:71], v[106:109], v[72:75], v[68:71]
	v_cndmask_b32_e32 v121, v101, v75, vcc
	v_cndmask_b32_e32 v120, v100, v74, vcc
	v_cndmask_b32_e32 v119, v99, v73, vcc
	v_cndmask_b32_e32 v118, v98, v72, vcc
	v_mfma_f32_16x16x32_bf16 v[64:67], v[106:109], v[98:101], v[64:67]
	s_waitcnt lgkmcnt(1)
	v_cndmask_b32_e32 v75, v117, v113, vcc
	v_cndmask_b32_e32 v74, v116, v112, vcc
	v_cndmask_b32_e32 v73, v115, v111, vcc
	v_mfma_f32_16x16x32_bf16 v[94:97], v[102:105], v[118:121], v[94:97]
	ds_read_b128 v[102:105], v127 offset:34880
	v_cndmask_b32_e32 v72, v114, v110, vcc
	v_mov_b32_e32 v84, v224
	s_waitcnt lgkmcnt(0)
	v_mfma_f32_16x16x32_bf16 v[68:71], v[102:105], v[110:113], v[68:71]
	v_and_b32_e32 v80, -16, v85
	v_and_b32_e32 v85, 15, v84
	v_mfma_f32_16x16x32_bf16 v[72:75], v[122:125], v[72:75], v[94:97]
	v_mul_u32_u24_e32 v85, 0x110, v85
	v_lshl_or_b32 v79, v79, 2, v80
	v_lshlrev_b32_e32 v80, 5, v126
	v_ashrrev_i32_e32 v94, 2, v84
	v_mfma_f32_16x16x32_bf16 v[64:67], v[102:105], v[114:117], v[64:67]
	v_lshlrev_b32_e32 v94, 1, v94
	v_and_b32_e32 v94, 0xffffffe0, v94
	v_lshrrev_b32_e32 v84, 1, v84
	v_add_u32_e32 v94, s16, v94
	v_and_b32_e32 v84, 24, v84
	v_add3_u32 v94, v94, v84, v85
	v_cvt_pk_bf16_f32 v85, v70, v71
	v_cvt_pk_bf16_f32 v84, v68, v69
	ds_write_b64 v94, v[84:85]
	v_cvt_pk_bf16_f32 v85, v66, v67
	v_cvt_pk_bf16_f32 v84, v64, v65
	ds_write_b64 v94, v[84:85] offset:4352
	v_lshl_add_u64 v[84:85], s[6:7], 0, v[80:81]
	v_lshlrev_b32_e32 v80, 1, v93
	v_lshl_add_u64 v[84:85], v[84:85], 0, v[80:81]
	v_cmp_gt_i32_e32 vcc, 64, v79
	s_add_i32 s8, s18, s33
	v_add_u32_e32 v94, s8, v79
	v_add_u32_e32 v94, 0x51, v94
	v_ashrrev_i32_e32 v95, 31, v94
	v_lshlrev_b64 v[94:95], 12, v[94:95]
	v_lshl_add_u64 v[94:95], v[84:85], 0, v[94:95]
	v_cvt_pk_bf16_f32 v72, v72, v73
	v_cvt_pk_bf16_f32 v74, v74, v75
	s_mov_b64 s[98:99], 0x2000
	global_store_short v[94:95], v72, off offset:-4096
	global_store_short_d16_hi v[94:95], v72, off
	v_lshl_add_u64 v[94:95], v[94:95], 0, s[98:99]
	global_store_short v[94:95], v74, off offset:-4096
	global_store_short_d16_hi v[94:95], v74, off
	s_cmpk_eq_i32 s33, 0x1f80
	s_cbranch_scc1 .LBB0_4350
	s_waitcnt vmcnt(17)
	ds_write_b128 v86, v[32:35]
	s_waitcnt vmcnt(16)
	ds_write_b128 v86, v[36:39] offset:8704
	s_waitcnt vmcnt(15)
	ds_write_b128 v86, v[40:43] offset:17408
	s_waitcnt vmcnt(14)
	ds_write_b128 v86, v[44:47] offset:26112
	s_waitcnt vmcnt(13)
	ds_write_b128 v88, v[48:51]
	s_waitcnt vmcnt(12)
	ds_write_b128 v89, v[52:55] offset:9216
	s_waitcnt vmcnt(11)
	ds_write_b128 v90, v[60:63]
	s_and_saveexec_b64 s[12:13], s[2:3]
	s_cbranch_execz .LBB0_4365
	s_waitcnt vmcnt(10)
	ds_write_b128 v87, v[56:59] offset:62464
; __device__ __forceinline__ void step_part1(char* sm, int off_ut, f32x4& o) {
;   const int tid_ = opq(threadIdx.x);
;   const int lane = tid_ & 63, w = tid_ >> 6, r = lane & 15, q = lane >> 4;
;   const int mj = w >> 1, nd = w & 1;
;   const bfraw* wl = (const bfraw*)(sm + L_W);
;   const bfraw* qg = (const bfraw*)(sm + L_QG);
;   const bfraw* uT = (const bfraw*)(sm + off_ut);
;   const bfraw* St = (const bfraw*)(sm + L_ST);
;   bfraw* dltT = (bfraw*)(sm + L_DLT);
;   f32x4 dl = (f32x4){0.f, 0.f, 0.f, 0.f};
;   o = (f32x4){0.f, 0.f, 0.f, 0.f};
; #pragma unroll
;   for (int kk = 0; kk < 4; ++kk) {
;     bf16x8 sb = *(const bf16x8*)(St + (nd * 16 + r) * 136 + kk * 32 + q * 8);
;     bf16x8 aw = *(const bf16x8*)(wl + (mj * 16 + r) * 136 + kk * 32 + q * 8);
;     bf16x8 aq = *(const bf16x8*)(qg + (mj * 16 + r) * 136 + kk * 32 + q * 8);
;     dl = mfma16(aw, sb, dl);
;     o = mfma16(aq, sb, o);
;   }
;   uint2 uv = *(const uint2*)(uT + (nd * 16 + r) * 72 + mj * 16 + q * 4);
;   uint2 dv;
;   dv.x = pack2(lo2f(uv.x) - dl[0], hi2f(uv.x) - dl[1]);
;   dv.y = pack2(lo2f(uv.y) - dl[2], hi2f(uv.y) - dl[3]);
;   *(uint2*)(dltT + (nd * 16 + r) * 72 + mj * 16 + q * 4) = dv;
; }
; __device__ __forceinline__ void step_part2(const Params& p, char* sm, int off_kgt, int off_qk, int h, int s, int grow0, int nvalid,
;                                            float gl, f32x4& o, f32x4 (&S)[2]) {
;   const int tid_ = opq(threadIdx.x);
;   const int lane = tid_ & 63, w = tid_ >> 6, r = lane & 15, q = lane >> 4;
;   const int mj = w >> 1, nd = w & 1;
;   const bfraw* kgT = (const bfraw*)(sm + off_kgt);
;   const bfraw* qk = (const bfraw*)(sm + off_qk);
;   const bfraw* dltT = (const bfraw*)(sm + L_DLT);
; #pragma unroll
;   for (int g = 0; g < 4; ++g) { S[0][g] *= gl; S[1][g] *= gl; }
; #pragma unroll
;   for (int kk = 0; kk < 2; ++kk) {
;     bf16x8 d0 = *(const bf16x8*)(dltT + (r) * 72 + kk * 32 + q * 8);
;     bf16x8 d1 = *(const bf16x8*)(dltT + (16 + r) * 72 + kk * 32 + q * 8);
;     bf16x8 aqk = *(const bf16x8*)(qk + (mj * 16 + r) * 72 + kk * 32 + q * 8);
;     bf16x8 ak = *(const bf16x8*)(kgT + (w * 16 + r) * 72 + kk * 32 + q * 8);
;     o = mfma16(aqk, nd ? d1 : d0, o);
;     S[0] = mfma16(ak, d0, S[0]);
;     S[1] = mfma16(ak, d1, S[1]);
;   }
;   write_St2(S, sm);
;   bfraw* OB = (bfraw*)(p.ws + WS_B1);
; #pragma unroll
;   for (int g = 0; g < 4; ++g) {
.LBB0_4365:
	s_or_b64 exec, exec, s[12:13]
	s_min_u32 s8, s34, 0x7d
	s_add_i32 s8, s8, s28
	s_lshl_b32 s8, s8, 2
	s_or_b32 s8, s8, s15
	s_waitcnt vmcnt(10)
	v_mov_b32_e32 v78, v225
	v_mad_u64_u32 v[56:57], s[12:13], s8, v91, v[82:83]
	v_add_co_u32_e32 v40, vcc, 0x2000, v56
	s_lshl_b32 s8, s8, 2
	s_nop 0
	v_addc_co_u32_e32 v41, vcc, 0, v57, vcc
	global_load_dwordx4 v[32:35], v[56:57], off
	global_load_dwordx4 v[36:39], v[40:41], off
	v_add_co_u32_e32 v40, vcc, 0x4000, v56
	v_mov_b32_e32 v72, s8
	s_nop 0
	v_addc_co_u32_e32 v41, vcc, 0, v57, vcc
	v_add_co_u32_e32 v44, vcc, 0x6000, v56
	s_nop 1
	v_addc_co_u32_e32 v45, vcc, 0, v57, vcc
	v_add_co_u32_e32 v48, vcc, 0x8000, v56
	global_load_dwordx4 v[40:43], v[40:41], off
	s_nop 0
	global_load_dwordx4 v[44:47], v[44:45], off
	v_addc_co_u32_e32 v49, vcc, 0, v57, vcc
	v_add_co_u32_e32 v52, vcc, 0xa000, v56
	s_nop 1
	v_addc_co_u32_e32 v53, vcc, 0, v57, vcc
	v_add_co_u32_e32 v58, vcc, 0xc000, v56
	global_load_dwordx4 v[48:51], v[48:49], off
	s_nop 0
	global_load_dwordx4 v[52:55], v[52:53], off
	v_addc_co_u32_e32 v59, vcc, 0, v57, vcc
	v_lshl_add_u64 v[56:57], v[56:57], 0, s[0:1]
	v_lshl_add_u64 v[56:57], v[76:77], 1, v[56:57]
	v_add_co_u32_e32 v56, vcc, 0xe000, v56
	s_nop 1
	v_addc_co_u32_e32 v57, vcc, 0, v57, vcc
	global_load_dwordx4 v[60:63], v[58:59], off
	s_nop 0
	global_load_dwordx4 v[56:59], v[56:57], off
	s_nop 0
	global_load_dword v225, v72, s[4:5]
	v_mov_b32_e32 v72, v224
	s_waitcnt lgkmcnt(0)
	s_barrier
	s_nop 0
	v_ashrrev_i32_e32 v118, 3, v72
	v_and_b32_e32 v79, 15, v72
	v_bfe_u32 v80, v72, 4, 2
	v_lshrrev_b32_e32 v85, 2, v72
	v_bfi_b32 v72, -16, v118, v72
	v_lshlrev_b32_e32 v93, 4, v80
	v_mul_lo_u32 v72, v72, s30
	v_add3_u32 v114, 0, v72, v93
	ds_read_b128 v[72:75], v114
	v_and_or_b32 v79, v85, 16, v79
	v_mul_u32_u24_e32 v85, 0x110, v79
	v_add3_u32 v85, s16, v85, v93
	ds_read_b128 v[94:97], v85
	ds_read_b128 v[98:101], v85 offset:64
	ds_read_b128 v[102:105], v114 offset:64
	s_waitcnt lgkmcnt(2)
	v_mfma_f32_16x16x32_bf16 v[72:75], v[72:75], v[94:97], 0
	ds_read_b128 v[106:109], v114 offset:17408
	ds_read_b128 v[110:113], v114 offset:17472
	v_mul_u32_u24_e32 v79, 0x48, v79
	v_lshlrev_b32_e32 v79, 1, v79
	s_waitcnt lgkmcnt(2)
	v_mfma_f32_16x16x32_bf16 v[72:75], v[102:105], v[98:101], v[72:75]
	ds_read_b128 v[102:105], v114 offset:128
	v_lshlrev_b32_e32 v80, 3, v80
	v_add_u32_e32 v93, 0, v79
	s_waitcnt lgkmcnt(2)
	v_mfma_f32_16x16x32_bf16 v[94:97], v[106:109], v[94:97], 0
	s_waitcnt lgkmcnt(1)
	v_mfma_f32_16x16x32_bf16 v[94:97], v[110:113], v[98:101], v[94:97]
	ds_read_b128 v[98:101], v85 offset:128
	ds_read_b128 v[106:109], v85 offset:192
	ds_read_b128 v[110:113], v114 offset:192
	v_and_b32_e32 v85, -16, v118
	v_lshlrev_b32_e32 v85, 1, v85
	s_waitcnt lgkmcnt(2)
	v_mfma_f32_16x16x32_bf16 v[72:75], v[102:105], v[98:101], v[72:75]
	ds_read_b128 v[102:105], v114 offset:17536
	ds_read_b128 v[114:117], v114 offset:17600
	v_add3_u32 v93, v93, v85, v80
	s_waitcnt lgkmcnt(1)
	v_mfma_f32_16x16x32_bf16 v[94:97], v[102:105], v[98:101], v[94:97]
	ds_read_b64 v[98:99], v93 offset:62464
	s_waitcnt lgkmcnt(0)
	v_lshlrev_b32_e32 v100, 16, v98
	v_mfma_f32_16x16x32_bf16 v[72:75], v[110:113], v[106:109], v[72:75]
	v_and_b32_e32 v101, 0xffff0000, v98
	v_lshlrev_b32_e32 v98, 16, v99
	v_and_b32_e32 v99, 0xffff0000, v99
	v_mfma_f32_16x16x32_bf16 v[94:97], v[114:117], v[106:109], v[94:97]
	s_nop 3
	v_add_f32_e64 v72, v100, -v72
	v_add_f32_e64 v73, v101, -v73
	v_pk_add_f32 v[74:75], v[98:99], v[74:75] neg_lo:[0,1] neg_hi:[0,1]
	v_cvt_pk_bf16_f32 v72, v72, v73
	v_cvt_pk_bf16_f32 v73, v74, v75
	v_add_u32_e32 v74, s17, v79
	v_add3_u32 v74, v74, v85, v80
	ds_write_b64 v74, v[72:73]
	v_mov_b32_e32 v72, v224
	s_waitcnt lgkmcnt(0)
	s_barrier
	s_nop 0
	v_ashrrev_i32_e32 v85, 3, v72
	v_ashrrev_i32_e32 v73, 6, v72
	v_and_b32_e32 v93, 15, v72
	v_bfe_u32 v80, v72, 4, 2
	v_bfi_b32 v72, -16, v85, v72
	v_lshlrev_b32_e32 v75, 4, v80
	v_mul_lo_u32 v72, v72, s31
	v_mul_u32_u24_e32 v74, 0x90, v93
	v_add3_u32 v122, s20, v72, v75
	v_lshl_or_b32 v72, v73, 4, v93
	v_and_b32_e32 v126, 1, v73
	v_add3_u32 v79, s17, v74, v75
	v_mul_lo_u32 v72, v72, s31
	v_add3_u32 v127, s19, v72, v75
	ds_read_b128 v[72:75], v79
	ds_read_b128 v[98:101], v79 offset:2304
	ds_read_b128 v[102:105], v122
	ds_read_b128 v[106:109], v127
	ds_read_b128 v[110:113], v79 offset:64
	ds_read_b128 v[114:117], v79 offset:2368
	v_cmp_eq_u32_e32 vcc, 0, v126
	ds_read_b128 v[122:125], v122 offset:64
	s_waitcnt vmcnt(18)
	v_pk_mul_f32 v[70:71], v[78:79], v[70:71] op_sel_hi:[0,1]
	s_waitcnt lgkmcnt(5)
	v_cndmask_b32_e32 v121, v101, v75, vcc
	v_cndmask_b32_e32 v120, v100, v74, vcc
	v_cndmask_b32_e32 v119, v99, v73, vcc
	v_cndmask_b32_e32 v118, v98, v72, vcc
	v_pk_mul_f32 v[68:69], v[78:79], v[68:69] op_sel_hi:[0,1]
	v_pk_mul_f32 v[66:67], v[78:79], v[66:67] op_sel_hi:[0,1]
	s_waitcnt lgkmcnt(4)
	v_mfma_f32_16x16x32_bf16 v[94:97], v[102:105], v[118:121], v[94:97]
	ds_read_b128 v[102:105], v127 offset:64
	v_pk_mul_f32 v[64:65], v[78:79], v[64:65] op_sel_hi:[0,1]
	v_mov_b32_e32 v78, v224
	s_waitcnt lgkmcnt(4)
	v_mfma_f32_16x16x32_bf16 v[68:71], v[106:109], v[72:75], v[68:71]
	s_waitcnt lgkmcnt(2)
	v_cndmask_b32_e32 v75, v117, v113, vcc
	v_cndmask_b32_e32 v74, v116, v112, vcc
	v_cndmask_b32_e32 v73, v115, v111, vcc
	v_mfma_f32_16x16x32_bf16 v[64:67], v[106:109], v[98:101], v[64:67]
	v_cndmask_b32_e32 v72, v114, v110, vcc
	v_and_b32_e32 v85, -16, v85
	s_waitcnt lgkmcnt(0)
	v_mfma_f32_16x16x32_bf16 v[68:71], v[102:105], v[110:113], v[68:71]
	v_and_b32_e32 v79, 15, v78
	v_mul_u32_u24_e32 v79, 0x110, v79
	v_lshl_or_b32 v85, v80, 2, v85
	v_mfma_f32_16x16x32_bf16 v[72:75], v[122:125], v[72:75], v[94:97]
	v_lshlrev_b32_e32 v80, 5, v126
	v_cmp_gt_i32_e32 vcc, 64, v85
	s_nop 0
	v_ashrrev_i32_e32 v94, 2, v78
	v_mfma_f32_16x16x32_bf16 v[64:67], v[102:105], v[114:117], v[64:67]
	v_lshlrev_b32_e32 v94, 1, v94
	v_and_b32_e32 v94, 0xffffffe0, v94
	v_lshrrev_b32_e32 v78, 1, v78
	v_add_u32_e32 v94, s16, v94
	v_and_b32_e32 v78, 24, v78
	v_add3_u32 v94, v94, v78, v79
	v_cvt_pk_bf16_f32 v79, v70, v71
	v_cvt_pk_bf16_f32 v78, v68, v69
	ds_write_b64 v94, v[78:79]
	v_cvt_pk_bf16_f32 v79, v66, v67
	v_cvt_pk_bf16_f32 v78, v64, v65
	ds_write_b64 v94, v[78:79] offset:4352
	v_lshl_add_u64 v[78:79], s[6:7], 0, v[80:81]
	v_lshlrev_b32_e32 v80, 1, v93
	v_lshl_add_u64 v[78:79], v[78:79], 0, v[80:81]
	s_add_i32 s8, s18, s33
	v_add_u32_e32 v94, s8, v85
	v_add_u32_e32 v94, 0x91, v94
	v_ashrrev_i32_e32 v95, 31, v94
	v_lshlrev_b64 v[94:95], 12, v[94:95]
	v_lshl_add_u64 v[94:95], v[78:79], 0, v[94:95]
	v_cvt_pk_bf16_f32 v72, v72, v73
	v_cvt_pk_bf16_f32 v74, v74, v75
	s_mov_b64 s[98:99], 0x2000
	global_store_short v[94:95], v72, off offset:-4096
	global_store_short_d16_hi v[94:95], v72, off
	v_lshl_add_u64 v[94:95], v[94:95], 0, s[98:99]
	global_store_short v[94:95], v74, off offset:-4096
	global_store_short_d16_hi v[94:95], v74, off
	s_andn2_b64 vcc, exec, s[10:11]
	s_addk_i32 s33, 0x80
	s_cbranch_vccnz .LBB0_4351
